# k06 + fused epilogue: per-wave buffer_inv acquire fence replaced by sc1 (L1-bypass) loads of the sc1-stored row partials
# speedup vs baseline: 1.0436x; 1.0257x over previous
.Lf4_nopre:
	s_waitcnt lgkmcnt(0)
	global_load_dwordx4 v[212:215], v[136:137], off
	global_load_dwordx4 v[216:219], v[136:137], off offset:64
	global_load_dwordx4 v[220:223], v[136:137], off offset:512
	global_load_dwordx4 v[224:227], v[136:137], off offset:576
	v_lshlrev_b64 v[204:205], 8, v[192:193]
	v_mov_b64_e32 v[206:207], 0x1000
	v_mov_b64_e32 v[208:209], 0x5000
	v_lshl_add_u64 v[204:205], v[132:133], 0, v[204:205]
	global_load_dwordx4 v[144:147], v[204:205], off sc1
	global_load_dwordx4 v[148:151], v[204:205], off offset:64 sc1
	global_load_dwordx4 v[152:155], v[204:205], off offset:128 sc1
	global_load_dwordx4 v[156:159], v[204:205], off offset:192 sc1
	v_lshl_add_u64 v[204:205], v[204:205], 0, v[206:207]
	global_load_dwordx4 v[160:163], v[204:205], off sc1
	global_load_dwordx4 v[164:167], v[204:205], off offset:64 sc1
	global_load_dwordx4 v[168:171], v[204:205], off offset:128 sc1
	global_load_dwordx4 v[172:175], v[204:205], off offset:192 sc1
	v_lshl_add_u64 v[204:205], v[204:205], 0, v[206:207]
	global_load_dwordx4 v[176:179], v[204:205], off sc1
	global_load_dwordx4 v[180:183], v[204:205], off offset:64 sc1
	global_load_dwordx4 v[184:187], v[204:205], off offset:128 sc1
	global_load_dwordx4 v[188:191], v[204:205], off offset:192 sc1
	s_mov_b32 s24, 32
	s_mov_b64 s[22:23], 0
	s_mov_b32 s46, s45
	s_waitcnt vmcnt(8)
	v_add_f32_e32 v144, v144, v145
	v_add_f32_e32 v146, v146, v147
	v_add_f32_e32 v148, v148, v149
	v_add_f32_e32 v150, v150, v151
	v_add_f32_e32 v152, v152, v153
	v_add_f32_e32 v154, v154, v155
	v_add_f32_e32 v156, v156, v157
	v_add_f32_e32 v158, v158, v159
	v_add_f32_e32 v144, v144, v146
	v_add_f32_e32 v148, v148, v150
	v_add_f32_e32 v152, v152, v154
	v_add_f32_e32 v156, v156, v158
	v_add_f32_e32 v144, v144, v148
	v_add_f32_e32 v152, v152, v156
	v_add_f32_e32 v228, v144, v152
	v_lshl_add_u64 v[204:205], v[204:205], 0, v[206:207]
	global_load_dwordx4 v[144:147], v[204:205], off sc1
	global_load_dwordx4 v[148:151], v[204:205], off offset:64 sc1
	global_load_dwordx4 v[152:155], v[204:205], off offset:128 sc1
	global_load_dwordx4 v[156:159], v[204:205], off offset:192 sc1
	s_waitcnt vmcnt(8)
	v_add_f32_e32 v160, v160, v161
	v_add_f32_e32 v162, v162, v163
	v_add_f32_e32 v164, v164, v165
	v_add_f32_e32 v166, v166, v167
	v_add_f32_e32 v168, v168, v169
	v_add_f32_e32 v170, v170, v171
	v_add_f32_e32 v172, v172, v173
	v_add_f32_e32 v174, v174, v175
	v_add_f32_e32 v160, v160, v162
	v_add_f32_e32 v164, v164, v166
	v_add_f32_e32 v168, v168, v170
	v_add_f32_e32 v172, v172, v174
	v_add_f32_e32 v160, v160, v164
	v_add_f32_e32 v168, v168, v172
	v_add_f32_e32 v229, v160, v168
	v_lshl_add_u64 v[204:205], v[204:205], 0, v[208:209]
	global_load_dwordx4 v[160:163], v[204:205], off sc1
	global_load_dwordx4 v[164:167], v[204:205], off offset:64 sc1
	global_load_dwordx4 v[168:171], v[204:205], off offset:128 sc1
	global_load_dwordx4 v[172:175], v[204:205], off offset:192 sc1
	s_waitcnt vmcnt(8)
	v_add_f32_e32 v176, v176, v177
	v_add_f32_e32 v178, v178, v179
	v_add_f32_e32 v180, v180, v181
	v_add_f32_e32 v182, v182, v183
	v_add_f32_e32 v184, v184, v185
	v_add_f32_e32 v186, v186, v187
	v_add_f32_e32 v188, v188, v189
	v_add_f32_e32 v190, v190, v191
	v_add_f32_e32 v176, v176, v178
	v_add_f32_e32 v180, v180, v182
	v_add_f32_e32 v184, v184, v186
	v_add_f32_e32 v188, v188, v190
	v_add_f32_e32 v176, v176, v180
	v_add_f32_e32 v184, v184, v188
	v_add_f32_e32 v230, v176, v184
	v_lshl_add_u64 v[204:205], v[204:205], 0, v[206:207]
	global_load_dwordx4 v[176:179], v[204:205], off sc1
	global_load_dwordx4 v[180:183], v[204:205], off offset:64 sc1
	global_load_dwordx4 v[184:187], v[204:205], off offset:128 sc1
	global_load_dwordx4 v[188:191], v[204:205], off offset:192 sc1
	s_waitcnt vmcnt(8)
	v_add_f32_e32 v144, v144, v145
	v_add_f32_e32 v146, v146, v147
	v_add_f32_e32 v148, v148, v149
	v_add_f32_e32 v150, v150, v151
	v_add_f32_e32 v152, v152, v153
	v_add_f32_e32 v154, v154, v155
	v_add_f32_e32 v156, v156, v157
	v_add_f32_e32 v158, v158, v159
	v_add_f32_e32 v144, v144, v146
	v_add_f32_e32 v148, v148, v150
	v_add_f32_e32 v152, v152, v154
	v_add_f32_e32 v156, v156, v158
	v_add_f32_e32 v144, v144, v148
	v_add_f32_e32 v152, v152, v156
	v_add_f32_e32 v231, v144, v152
	v_lshl_add_u64 v[204:205], v[204:205], 0, v[206:207]
	global_load_dwordx4 v[144:147], v[204:205], off sc1
	global_load_dwordx4 v[148:151], v[204:205], off offset:64 sc1
	global_load_dwordx4 v[152:155], v[204:205], off offset:128 sc1
	global_load_dwordx4 v[156:159], v[204:205], off offset:192 sc1
	s_waitcnt vmcnt(8)
	v_add_f32_e32 v160, v160, v161
	v_add_f32_e32 v162, v162, v163
	v_add_f32_e32 v164, v164, v165
	v_add_f32_e32 v166, v166, v167
	v_add_f32_e32 v168, v168, v169
	v_add_f32_e32 v170, v170, v171
	v_add_f32_e32 v172, v172, v173
	v_add_f32_e32 v174, v174, v175
	v_add_f32_e32 v160, v160, v162
	v_add_f32_e32 v164, v164, v166
	v_add_f32_e32 v168, v168, v170
	v_add_f32_e32 v172, v172, v174
	v_add_f32_e32 v160, v160, v164
	v_add_f32_e32 v168, v168, v172
	v_add_f32_e32 v232, v160, v168
	v_lshl_add_u64 v[204:205], v[204:205], 0, v[206:207]
	global_load_dwordx4 v[160:163], v[204:205], off sc1
	global_load_dwordx4 v[164:167], v[204:205], off offset:64 sc1
	global_load_dwordx4 v[168:171], v[204:205], off offset:128 sc1
	global_load_dwordx4 v[172:175], v[204:205], off offset:192 sc1
	s_waitcnt vmcnt(8)
	v_add_f32_e32 v176, v176, v177
	v_add_f32_e32 v178, v178, v179
	v_add_f32_e32 v180, v180, v181
	v_add_f32_e32 v182, v182, v183
	v_add_f32_e32 v184, v184, v185
	v_add_f32_e32 v186, v186, v187
	v_add_f32_e32 v188, v188, v189
	v_add_f32_e32 v190, v190, v191
	v_add_f32_e32 v176, v176, v178
	v_add_f32_e32 v180, v180, v182
	v_add_f32_e32 v184, v184, v186
	v_add_f32_e32 v188, v188, v190
	v_add_f32_e32 v176, v176, v180
	v_add_f32_e32 v184, v184, v188
	v_add_f32_e32 v233, v176, v184
	s_waitcnt vmcnt(4)
	v_add_f32_e32 v144, v144, v145
	v_add_f32_e32 v146, v146, v147
	v_add_f32_e32 v148, v148, v149
	v_add_f32_e32 v150, v150, v151
	v_add_f32_e32 v152, v152, v153
	v_add_f32_e32 v154, v154, v155
	v_add_f32_e32 v156, v156, v157
	v_add_f32_e32 v158, v158, v159
	v_add_f32_e32 v144, v144, v146
	v_add_f32_e32 v148, v148, v150
	v_add_f32_e32 v152, v152, v154
	v_add_f32_e32 v156, v156, v158
	v_add_f32_e32 v144, v144, v148
	v_add_f32_e32 v152, v152, v156
	v_add_f32_e32 v234, v144, v152
	s_waitcnt vmcnt(0)
	v_add_f32_e32 v160, v160, v161
	v_add_f32_e32 v162, v162, v163
	v_add_f32_e32 v164, v164, v165
	v_add_f32_e32 v166, v166, v167
	v_add_f32_e32 v168, v168, v169
	v_add_f32_e32 v170, v170, v171
	v_add_f32_e32 v172, v172, v173
	v_add_f32_e32 v174, v174, v175
	v_add_f32_e32 v160, v160, v162
	v_add_f32_e32 v164, v164, v166
	v_add_f32_e32 v168, v168, v170
	v_add_f32_e32 v172, v172, v174
	v_add_f32_e32 v160, v160, v164
	v_add_f32_e32 v168, v168, v172
	v_add_f32_e32 v235, v160, v168
	ds_bpermute_b32 v144, v202, v228
	ds_bpermute_b32 v145, v202, v229
	ds_bpermute_b32 v146, v202, v230
	ds_bpermute_b32 v147, v202, v231
	ds_bpermute_b32 v148, v202, v232
	ds_bpermute_b32 v149, v202, v233
	ds_bpermute_b32 v150, v202, v234
	ds_bpermute_b32 v151, v202, v235
	s_waitcnt lgkmcnt(0)
	v_add_f32_e32 v228, v228, v144
	v_add_f32_e32 v229, v229, v145
	v_add_f32_e32 v230, v230, v146
	v_add_f32_e32 v231, v231, v147
	v_add_f32_e32 v232, v232, v148
	v_add_f32_e32 v233, v233, v149
	v_add_f32_e32 v234, v234, v150
	v_add_f32_e32 v235, v235, v151
	ds_bpermute_b32 v144, v203, v228
	ds_bpermute_b32 v145, v203, v229
	ds_bpermute_b32 v146, v203, v230
	ds_bpermute_b32 v147, v203, v231
	ds_bpermute_b32 v148, v203, v232
	ds_bpermute_b32 v149, v203, v233
	ds_bpermute_b32 v150, v203, v234
	ds_bpermute_b32 v151, v203, v235
	s_waitcnt lgkmcnt(0)
	v_add_f32_e32 v228, v228, v144
	v_add_f32_e32 v229, v229, v145
	v_add_f32_e32 v230, v230, v146
	v_add_f32_e32 v231, v231, v147
	v_add_f32_e32 v232, v232, v148
	v_add_f32_e32 v233, v233, v149
	v_add_f32_e32 v234, v234, v150
	v_add_f32_e32 v235, v235, v151
	v_fmamk_f32 v228, v228, 0x39800000, v200
	v_fmamk_f32 v229, v229, 0x39800000, v200
	v_fmamk_f32 v230, v230, 0x39800000, v200
	v_fmamk_f32 v231, v231, 0x39800000, v200
	v_fmamk_f32 v232, v232, 0x39800000, v200
	v_fmamk_f32 v233, v233, 0x39800000, v200
	v_fmamk_f32 v234, v234, 0x39800000, v200
	v_fmamk_f32 v235, v235, 0x39800000, v200
	v_rsq_f32_e32 v228, v228
	v_rsq_f32_e32 v229, v229
	v_rsq_f32_e32 v230, v230
	v_rsq_f32_e32 v231, v231
	v_rsq_f32_e32 v232, v232
	v_rsq_f32_e32 v233, v233
	v_rsq_f32_e32 v234, v234
	v_rsq_f32_e32 v235, v235
	v_lshlrev_b64 v[204:205], 14, v[192:193]
	v_mov_b64_e32 v[206:207], 0x40000
	v_mov_b64_e32 v[208:209], 0x140000
	v_lshl_add_u64 v[204:205], v[138:139], 0, v[204:205]
	v_mul_f32_e32 v124, v228, v124
	v_mul_f32_e32 v125, v228, v125
	v_mul_f32_e32 v126, v228, v126
	v_mul_f32_e32 v127, v228, v127
	v_mul_f32_e32 v120, v228, v120
	v_mul_f32_e32 v121, v228, v121
	v_mul_f32_e32 v122, v228, v122
	v_mul_f32_e32 v123, v228, v123
	v_mul_f32_e32 v116, v228, v116
	v_mul_f32_e32 v117, v228, v117
	v_mul_f32_e32 v118, v228, v118
	v_mul_f32_e32 v119, v228, v119
	v_mul_f32_e32 v112, v228, v112
	v_mul_f32_e32 v113, v228, v113
	v_mul_f32_e32 v114, v228, v114
	v_mul_f32_e32 v115, v228, v115
	v_pk_mul_f32 v[124:125], v[212:213], v[124:125]
	v_pk_mul_f32 v[126:127], v[214:215], v[126:127]
	v_pk_mul_f32 v[120:121], v[216:217], v[120:121]
	v_pk_mul_f32 v[122:123], v[218:219], v[122:123]
	v_pk_mul_f32 v[116:117], v[220:221], v[116:117]
	v_pk_mul_f32 v[118:119], v[222:223], v[118:119]
	v_pk_mul_f32 v[112:113], v[224:225], v[112:113]
	v_pk_mul_f32 v[114:115], v[226:227], v[114:115]
	global_store_dwordx4 v[204:205], v[124:127], off
	global_store_dwordx4 v[204:205], v[120:123], off offset:64
	global_store_dwordx4 v[204:205], v[116:119], off offset:512
	global_store_dwordx4 v[204:205], v[112:115], off offset:576
	v_mul_f32_e32 v108, v229, v108
	v_mul_f32_e32 v109, v229, v109
	v_mul_f32_e32 v110, v229, v110
	v_mul_f32_e32 v111, v229, v111
	v_mul_f32_e32 v104, v229, v104
	v_mul_f32_e32 v105, v229, v105
	v_mul_f32_e32 v106, v229, v106
	v_mul_f32_e32 v107, v229, v107
	v_mul_f32_e32 v100, v229, v100
	v_mul_f32_e32 v101, v229, v101
	v_mul_f32_e32 v102, v229, v102
	v_mul_f32_e32 v103, v229, v103
	v_mul_f32_e32 v96, v229, v96
	v_mul_f32_e32 v97, v229, v97
	v_mul_f32_e32 v98, v229, v98
	v_mul_f32_e32 v99, v229, v99
	v_pk_mul_f32 v[108:109], v[212:213], v[108:109]
	v_pk_mul_f32 v[110:111], v[214:215], v[110:111]
	v_pk_mul_f32 v[104:105], v[216:217], v[104:105]
	v_pk_mul_f32 v[106:107], v[218:219], v[106:107]
	v_pk_mul_f32 v[100:101], v[220:221], v[100:101]
	v_pk_mul_f32 v[102:103], v[222:223], v[102:103]
	v_pk_mul_f32 v[96:97], v[224:225], v[96:97]
	v_pk_mul_f32 v[98:99], v[226:227], v[98:99]
	v_lshl_add_u64 v[204:205], v[204:205], 0, v[206:207]
	global_store_dwordx4 v[204:205], v[108:111], off
	global_store_dwordx4 v[204:205], v[104:107], off offset:64
	global_store_dwordx4 v[204:205], v[100:103], off offset:512
	global_store_dwordx4 v[204:205], v[96:99], off offset:576
	v_mul_f32_e32 v92, v230, v92
	v_mul_f32_e32 v93, v230, v93
	v_mul_f32_e32 v94, v230, v94
	v_mul_f32_e32 v95, v230, v95
	v_mul_f32_e32 v88, v230, v88
	v_mul_f32_e32 v89, v230, v89
	v_mul_f32_e32 v90, v230, v90
	v_mul_f32_e32 v91, v230, v91
	v_mul_f32_e32 v84, v230, v84
	v_mul_f32_e32 v85, v230, v85
	v_mul_f32_e32 v86, v230, v86
	v_mul_f32_e32 v87, v230, v87
	v_mul_f32_e32 v80, v230, v80
	v_mul_f32_e32 v81, v230, v81
	v_mul_f32_e32 v82, v230, v82
	v_mul_f32_e32 v83, v230, v83
	v_pk_mul_f32 v[92:93], v[212:213], v[92:93]
	v_pk_mul_f32 v[94:95], v[214:215], v[94:95]
	v_pk_mul_f32 v[88:89], v[216:217], v[88:89]
	v_pk_mul_f32 v[90:91], v[218:219], v[90:91]
	v_pk_mul_f32 v[84:85], v[220:221], v[84:85]
	v_pk_mul_f32 v[86:87], v[222:223], v[86:87]
	v_pk_mul_f32 v[80:81], v[224:225], v[80:81]
	v_pk_mul_f32 v[82:83], v[226:227], v[82:83]
	v_lshl_add_u64 v[204:205], v[204:205], 0, v[206:207]
	global_store_dwordx4 v[204:205], v[92:95], off
	global_store_dwordx4 v[204:205], v[88:91], off offset:64
	global_store_dwordx4 v[204:205], v[84:87], off offset:512
	global_store_dwordx4 v[204:205], v[80:83], off offset:576
	v_mul_f32_e32 v76, v231, v76
	v_mul_f32_e32 v77, v231, v77
	v_mul_f32_e32 v78, v231, v78
	v_mul_f32_e32 v79, v231, v79
	v_mul_f32_e32 v72, v231, v72
	v_mul_f32_e32 v73, v231, v73
	v_mul_f32_e32 v74, v231, v74
	v_mul_f32_e32 v75, v231, v75
	v_mul_f32_e32 v68, v231, v68
	v_mul_f32_e32 v69, v231, v69
	v_mul_f32_e32 v70, v231, v70
	v_mul_f32_e32 v71, v231, v71
	v_mul_f32_e32 v64, v231, v64
	v_mul_f32_e32 v65, v231, v65
	v_mul_f32_e32 v66, v231, v66
	v_mul_f32_e32 v67, v231, v67
	v_pk_mul_f32 v[76:77], v[212:213], v[76:77]
	v_pk_mul_f32 v[78:79], v[214:215], v[78:79]
	v_pk_mul_f32 v[72:73], v[216:217], v[72:73]
	v_pk_mul_f32 v[74:75], v[218:219], v[74:75]
	v_pk_mul_f32 v[68:69], v[220:221], v[68:69]
	v_pk_mul_f32 v[70:71], v[222:223], v[70:71]
	v_pk_mul_f32 v[64:65], v[224:225], v[64:65]
	v_pk_mul_f32 v[66:67], v[226:227], v[66:67]
	v_lshl_add_u64 v[204:205], v[204:205], 0, v[206:207]
	global_store_dwordx4 v[204:205], v[76:79], off
	global_store_dwordx4 v[204:205], v[72:75], off offset:64
	global_store_dwordx4 v[204:205], v[68:71], off offset:512
	global_store_dwordx4 v[204:205], v[64:67], off offset:576
	v_mul_f32_e32 v60, v232, v60
	v_mul_f32_e32 v61, v232, v61
	v_mul_f32_e32 v62, v232, v62
	v_mul_f32_e32 v63, v232, v63
	v_mul_f32_e32 v56, v232, v56
	v_mul_f32_e32 v57, v232, v57
	v_mul_f32_e32 v58, v232, v58
	v_mul_f32_e32 v59, v232, v59
	v_mul_f32_e32 v52, v232, v52
	v_mul_f32_e32 v53, v232, v53
	v_mul_f32_e32 v54, v232, v54
	v_mul_f32_e32 v55, v232, v55
	v_mul_f32_e32 v48, v232, v48
	v_mul_f32_e32 v49, v232, v49
	v_mul_f32_e32 v50, v232, v50
	v_mul_f32_e32 v51, v232, v51
	v_pk_mul_f32 v[60:61], v[212:213], v[60:61]
	v_pk_mul_f32 v[62:63], v[214:215], v[62:63]
	v_pk_mul_f32 v[56:57], v[216:217], v[56:57]
	v_pk_mul_f32 v[58:59], v[218:219], v[58:59]
	v_pk_mul_f32 v[52:53], v[220:221], v[52:53]
	v_pk_mul_f32 v[54:55], v[222:223], v[54:55]
	v_pk_mul_f32 v[48:49], v[224:225], v[48:49]
	v_pk_mul_f32 v[50:51], v[226:227], v[50:51]
	v_lshl_add_u64 v[204:205], v[204:205], 0, v[208:209]
	global_store_dwordx4 v[204:205], v[60:63], off
	global_store_dwordx4 v[204:205], v[56:59], off offset:64
	global_store_dwordx4 v[204:205], v[52:55], off offset:512
	global_store_dwordx4 v[204:205], v[48:51], off offset:576
	v_mul_f32_e32 v44, v233, v44
	v_mul_f32_e32 v45, v233, v45
	v_mul_f32_e32 v46, v233, v46
	v_mul_f32_e32 v47, v233, v47
	v_mul_f32_e32 v40, v233, v40
	v_mul_f32_e32 v41, v233, v41
	v_mul_f32_e32 v42, v233, v42
	v_mul_f32_e32 v43, v233, v43
	v_mul_f32_e32 v36, v233, v36
	v_mul_f32_e32 v37, v233, v37
	v_mul_f32_e32 v38, v233, v38
	v_mul_f32_e32 v39, v233, v39
	v_mul_f32_e32 v32, v233, v32
	v_mul_f32_e32 v33, v233, v33
	v_mul_f32_e32 v34, v233, v34
	v_mul_f32_e32 v35, v233, v35
	v_pk_mul_f32 v[44:45], v[212:213], v[44:45]
	v_pk_mul_f32 v[46:47], v[214:215], v[46:47]
	v_pk_mul_f32 v[40:41], v[216:217], v[40:41]
	v_pk_mul_f32 v[42:43], v[218:219], v[42:43]
	v_pk_mul_f32 v[36:37], v[220:221], v[36:37]
	v_pk_mul_f32 v[38:39], v[222:223], v[38:39]
	v_pk_mul_f32 v[32:33], v[224:225], v[32:33]
	v_pk_mul_f32 v[34:35], v[226:227], v[34:35]
	v_lshl_add_u64 v[204:205], v[204:205], 0, v[206:207]
	global_store_dwordx4 v[204:205], v[44:47], off
	global_store_dwordx4 v[204:205], v[40:43], off offset:64
	global_store_dwordx4 v[204:205], v[36:39], off offset:512
	global_store_dwordx4 v[204:205], v[32:35], off offset:576
	v_mul_f32_e32 v28, v234, v28
	v_mul_f32_e32 v29, v234, v29
	v_mul_f32_e32 v30, v234, v30
	v_mul_f32_e32 v31, v234, v31
	v_mul_f32_e32 v24, v234, v24
	v_mul_f32_e32 v25, v234, v25
	v_mul_f32_e32 v26, v234, v26
	v_mul_f32_e32 v27, v234, v27
	v_mul_f32_e32 v20, v234, v20
	v_mul_f32_e32 v21, v234, v21
	v_mul_f32_e32 v22, v234, v22
	v_mul_f32_e32 v23, v234, v23
	v_mul_f32_e32 v16, v234, v16
	v_mul_f32_e32 v17, v234, v17
	v_mul_f32_e32 v18, v234, v18
	v_mul_f32_e32 v19, v234, v19
	v_pk_mul_f32 v[28:29], v[212:213], v[28:29]
	v_pk_mul_f32 v[30:31], v[214:215], v[30:31]
	v_pk_mul_f32 v[24:25], v[216:217], v[24:25]
	v_pk_mul_f32 v[26:27], v[218:219], v[26:27]
	v_pk_mul_f32 v[20:21], v[220:221], v[20:21]
	v_pk_mul_f32 v[22:23], v[222:223], v[22:23]
	v_pk_mul_f32 v[16:17], v[224:225], v[16:17]
	v_pk_mul_f32 v[18:19], v[226:227], v[18:19]
	v_lshl_add_u64 v[204:205], v[204:205], 0, v[206:207]
	global_store_dwordx4 v[204:205], v[28:31], off
	global_store_dwordx4 v[204:205], v[24:27], off offset:64
	global_store_dwordx4 v[204:205], v[20:23], off offset:512
	global_store_dwordx4 v[204:205], v[16:19], off offset:576
	v_mul_f32_e32 v12, v235, v12
	v_mul_f32_e32 v13, v235, v13
	v_mul_f32_e32 v14, v235, v14
	v_mul_f32_e32 v15, v235, v15
	v_mul_f32_e32 v8, v235, v8
	v_mul_f32_e32 v9, v235, v9
	v_mul_f32_e32 v10, v235, v10
	v_mul_f32_e32 v11, v235, v11
	v_mul_f32_e32 v4, v235, v4
	v_mul_f32_e32 v5, v235, v5
	v_mul_f32_e32 v6, v235, v6
	v_mul_f32_e32 v7, v235, v7
	v_mul_f32_e32 v0, v235, v0
	v_mul_f32_e32 v1, v235, v1
	v_mul_f32_e32 v2, v235, v2
	v_mul_f32_e32 v3, v235, v3
	v_pk_mul_f32 v[12:13], v[212:213], v[12:13]
	v_pk_mul_f32 v[14:15], v[214:215], v[14:15]
	v_pk_mul_f32 v[8:9], v[216:217], v[8:9]
	v_pk_mul_f32 v[10:11], v[218:219], v[10:11]
	v_pk_mul_f32 v[4:5], v[220:221], v[4:5]
	v_pk_mul_f32 v[6:7], v[222:223], v[6:7]
	v_pk_mul_f32 v[0:1], v[224:225], v[0:1]
	v_pk_mul_f32 v[2:3], v[226:227], v[2:3]
	v_lshl_add_u64 v[204:205], v[204:205], 0, v[206:207]
	global_store_dwordx4 v[204:205], v[12:15], off
	global_store_dwordx4 v[204:205], v[8:11], off offset:64
	global_store_dwordx4 v[204:205], v[4:7], off offset:512
	global_store_dwordx4 v[204:205], v[0:3], off offset:576
	s_cmpk_gt_u32 s10, 0xff
	s_cbranch_scc0 .Lf4_nopost
	s_barrier
